# attention Q fragments: coalesced row-major global loads staged through per-wave LDS then read into the MFMA B-operand layout (instead of 12 loads touching 32 rows x 32 B each)
# speedup vs baseline: 1.0001x; 1.0001x over previous
; #define LAS __attribute__((address_space(3)))
; DI int tid_opq() { int t = threadIdx.x; asm volatile("" : "+v"(t)); return t; }
; DI void attn_unit(LAS unsigned char* lds, const bf16_t* Q, const bf16_t* Kn, const bf16_t* Kpe, const bf16_t* Vt, bf16_t* O, int b, int h, int qb) {
;     const int tid = tid_opq(), wid = __builtin_amdgcn_readfirstlane(tid >> 6), lane = tid & 63, r32 = lane & 31, hi = lane >> 5;
;     LAS unsigned char* Ks = lds; LAS unsigned char* Vs = lds + 2 * KBUF;
;     const int qrow = b * 4096 + qb * 512 + wid * 64 + r32;
;     bf16x8 qf[2][6];
; #pragma unroll
;     for (int j = 0; j < 2; ++j)
; #pragma unroll
;         for (int s = 0; s < 6; ++s) qf[j][s] = *(const bf16x8*)(Q + (size_t)(qrow + 32 * j) * 1536 + h * 96 + 16 * s + 8 * hi);
;     const bf16_t* kn_b = Kn + (size_t)(b * 16 + h) * 4096 * 64; const bf16_t* kp_b = Kpe + (size_t)b * 4096 * 32; const bf16_t* vt_b = Vt + (size_t)(b * 16 + h) * 64 * 4096;
;     const unsigned kn_o = (unsigned)((tid >> 3) * 64 + (tid & 7) * 8), kp_o = (unsigned)((tid >> 2) * 32 + (tid & 3) * 8), vt_o = (unsigned)((tid >> 3) * 4096 + (tid & 7) * 8);
;     ...
;     const int kn_l = (tid >> 3) * KPITCH + (tid & 7) * 16, kp_l = (tid >> 2) * KPITCH + 128 + (tid & 3) * 16, vt_l = (tid >> 3) * VPITCH + (tid & 7) * 16;
;     u32x4 rk = *(const u32x4*)kn_g, rp = (u32x4){0, 0, 0, 0}, rv = *(const u32x4*)vt_g;
.LBB0_1114:
	s_ashr_i32 s6, s9, 7
	s_bfe_u32 s8, s9, 0x40003
	v_mov_b32_e32 v12, v232
	s_lshl_b32 s9, s9, 9
	s_lshl_b32 s7, s6, 12
	v_readfirstlane_b32 s2, v12
	s_and_b32 s9, s9, 0xe00
	s_or_b32 s9, s9, s7
	s_and_b32 s7, s2, 0xffffffc0
	v_and_b32_e32 v226, 31, v12
	s_add_i32 s7, s7, s9
	v_or_b32_e32 v4, s7, v226
	s_mul_i32 s7, s8, 0xc0
	v_bfe_u32 v68, v12, 5, 1
	s_add_u32 s14, s54, s7
	s_addc_u32 s15, s55, 0
	v_lshlrev_b32_e32 v188, 4, v68
	v_lshl_add_u64 v[0:1], s[14:15], 0, v[188:189]
	v_sub_u32_e32 v40, v4, v226
	v_add_u32_e32 v41, 0, v233
	v_mul_u32_u24_e32 v42, 0xaaab, v41
	v_lshrrev_b32_e32 v42, 19, v42
	v_mul_u32_u24_e32 v43, 12, v42
	v_sub_u32_e32 v43, v41, v43
	v_lshlrev_b32_e32 v44, 4, v43
	v_mov_b32_e32 v45, 0
	v_lshl_add_u64 v[46:47], s[14:15], 0, v[44:45]
	v_add_u32_e32 v42, v40, v42
	v_mad_i64_i32 v[16:17], vcc, v42, s73, v[46:47]
	v_add_u32_e32 v42, 32, v42
	v_mad_i64_i32 v[28:29], vcc, v42, s73, v[46:47]
	v_add_u32_e32 v41, 64, v233
	v_mul_u32_u24_e32 v42, 0xaaab, v41
	v_lshrrev_b32_e32 v42, 19, v42
	v_mul_u32_u24_e32 v43, 12, v42
	v_sub_u32_e32 v43, v41, v43
	v_lshlrev_b32_e32 v44, 4, v43
	v_mov_b32_e32 v45, 0
	v_lshl_add_u64 v[46:47], s[14:15], 0, v[44:45]
	v_add_u32_e32 v42, v40, v42
	v_mad_i64_i32 v[18:19], vcc, v42, s73, v[46:47]
	v_add_u32_e32 v42, 32, v42
	v_mad_i64_i32 v[30:31], vcc, v42, s73, v[46:47]
	v_add_u32_e32 v41, 128, v233
	v_mul_u32_u24_e32 v42, 0xaaab, v41
	v_lshrrev_b32_e32 v42, 19, v42
	v_mul_u32_u24_e32 v43, 12, v42
	v_sub_u32_e32 v43, v41, v43
	v_lshlrev_b32_e32 v44, 4, v43
	v_mov_b32_e32 v45, 0
	v_lshl_add_u64 v[46:47], s[14:15], 0, v[44:45]
	v_add_u32_e32 v42, v40, v42
	v_mad_i64_i32 v[20:21], vcc, v42, s73, v[46:47]
	v_add_u32_e32 v42, 32, v42
	v_mad_i64_i32 v[32:33], vcc, v42, s73, v[46:47]
	v_add_u32_e32 v41, 192, v233
	v_mul_u32_u24_e32 v42, 0xaaab, v41
	v_lshrrev_b32_e32 v42, 19, v42
	v_mul_u32_u24_e32 v43, 12, v42
	v_sub_u32_e32 v43, v41, v43
	v_lshlrev_b32_e32 v44, 4, v43
	v_mov_b32_e32 v45, 0
	v_lshl_add_u64 v[46:47], s[14:15], 0, v[44:45]
	v_add_u32_e32 v42, v40, v42
	v_mad_i64_i32 v[22:23], vcc, v42, s73, v[46:47]
	v_add_u32_e32 v42, 32, v42
	v_mad_i64_i32 v[34:35], vcc, v42, s73, v[46:47]
	v_add_u32_e32 v41, 256, v233
	v_mul_u32_u24_e32 v42, 0xaaab, v41
	v_lshrrev_b32_e32 v42, 19, v42
	v_mul_u32_u24_e32 v43, 12, v42
	v_sub_u32_e32 v43, v41, v43
	v_lshlrev_b32_e32 v44, 4, v43
	v_mov_b32_e32 v45, 0
	v_lshl_add_u64 v[46:47], s[14:15], 0, v[44:45]
	v_add_u32_e32 v42, v40, v42
	v_mad_i64_i32 v[24:25], vcc, v42, s73, v[46:47]
	v_add_u32_e32 v42, 32, v42
	v_mad_i64_i32 v[36:37], vcc, v42, s73, v[46:47]
	v_add_u32_e32 v41, 320, v233
	v_mul_u32_u24_e32 v42, 0xaaab, v41
	v_lshrrev_b32_e32 v42, 19, v42
	v_mul_u32_u24_e32 v43, 12, v42
	v_sub_u32_e32 v43, v41, v43
	v_lshlrev_b32_e32 v44, 4, v43
	v_mov_b32_e32 v45, 0
	v_lshl_add_u64 v[46:47], s[14:15], 0, v[44:45]
	v_add_u32_e32 v42, v40, v42
	v_mad_i64_i32 v[26:27], vcc, v42, s73, v[46:47]
	v_add_u32_e32 v42, 32, v42
	v_mad_i64_i32 v[38:39], vcc, v42, s73, v[46:47]
	v_mad_i64_i32 v[2:3], s[14:15], v4, s73, v[0:1]
	v_or_b32_e32 v4, 32, v4
	v_mad_i64_i32 v[0:1], s[14:15], v4, s73, v[0:1]
	s_lshl_b32 s7, s6, 4
	s_or_b32 s14, s7, s8
	s_ashr_i32 s15, s14, 31
	s_lshl_b64 s[14:15], s[14:15], 19
	s_add_u32 s20, s64, s14
	s_addc_u32 s21, s65, s15
	s_ashr_i32 s7, s6, 31
	s_lshl_b64 s[6:7], s[6:7], 18
	global_load_dwordx4 v[80:83], v[16:17], off
	global_load_dwordx4 v[84:87], v[18:19], off
	global_load_dwordx4 v[88:91], v[20:21], off
	global_load_dwordx4 v[92:95], v[22:23], off
	global_load_dwordx4 v[96:99], v[24:25], off
	global_load_dwordx4 v[104:107], v[28:29], off
	global_load_dwordx4 v[108:111], v[30:31], off
	global_load_dwordx4 v[112:115], v[32:33], off
	global_load_dwordx4 v[116:119], v[34:35], off
	global_load_dwordx4 v[120:123], v[36:37], off
	s_add_u32 s22, s68, s6
	v_ashrrev_i32_e32 v9, 3, v12
	v_and_b32_e32 v8, 7, v12
	s_addc_u32 s23, s69, s7
	v_lshlrev_b32_e32 v218, 6, v9
	v_lshlrev_b32_e32 v219, 3, v8
	s_add_u32 s24, s76, s14
	v_or_b32_e32 v188, v218, v219
	v_lshlrev_b32_e32 v220, 12, v9
	s_addc_u32 s25, s77, s15
	v_or_b32_e32 v10, v220, v219
	v_lshl_add_u64 v[4:5], v[188:189], 1, s[20:21]
	v_mov_b32_e32 v11, v189
	global_load_dwordx4 v[124:127], v[38:39], off
	s_nop 0
	global_load_dwordx4 v[4:7], v[4:5], off
	v_lshl_add_u64 v[66:67], v[10:11], 1, s[24:25]
	global_load_dwordx4 v[100:103], v[26:27], off
	s_nop 0
	global_load_dwordx4 v[0:3], v[66:67], off
	v_ashrrev_i32_e32 v10, 2, v12
	v_and_b32_e32 v11, 3, v12
	s_movk_i32 s6, 0xff
	v_lshlrev_b32_e32 v221, 5, v10
	v_lshlrev_b32_e32 v222, 3, v11
	v_cmp_lt_i32_e64 s[16:17], s6, v12
	s_movk_i32 s6, 0x100
	v_or_b32_e32 v64, v221, v222
	v_cmp_gt_i32_e64 s[14:15], s6, v12
	s_waitcnt vmcnt(30)
	v_mov_b32_e32 v176, v189
	v_mov_b32_e32 v177, v189
	v_mov_b32_e32 v178, v189
	v_mov_b32_e32 v179, v189
	s_and_saveexec_b64 s[6:7], s[14:15]
	s_cbranch_execz .LBB0_1116
	v_mov_b32_e32 v65, v189
	v_lshl_add_u64 v[12:13], v[64:65], 1, s[22:23]
	global_load_dwordx4 v[176:179], v[12:13], off

; #define LAS __attribute__((address_space(3)))
; DI void attn_unit(LAS unsigned char* lds, const bf16_t* Q, const bf16_t* Kn, const bf16_t* Kpe, const bf16_t* Vt, bf16_t* O, int b, int h, int qb) {
;     ...
;     bf16x8 qf[2][6];
; #pragma unroll
;     for (int j = 0; j < 2; ++j)
; #pragma unroll
;         for (int s = 0; s < 6; ++s) qf[j][s] = *(const bf16x8*)(Q + (size_t)(qrow + 32 * j) * 1536 + h * 96 + 16 * s + 8 * hi);
;     const bf16_t* kn_b = Kn + (size_t)(b * 16 + h) * 4096 * 64; const bf16_t* kp_b = Kpe + (size_t)b * 4096 * 32; const bf16_t* vt_b = Vt + (size_t)(b * 16 + h) * 64 * 4096;
;     const unsigned kn_o = (unsigned)((tid >> 3) * 64 + (tid & 7) * 8), kp_o = (unsigned)((tid >> 2) * 32 + (tid & 3) * 8), vt_o = (unsigned)((tid >> 3) * 4096 + (tid & 7) * 8);
;     ...
;     const int kn_l = (tid >> 3) * KPITCH + (tid & 7) * 16, kp_l = (tid >> 2) * KPITCH + 128 + (tid & 3) * 16, vt_l = (tid >> 3) * VPITCH + (tid & 7) * 16;
;     u32x4 rk = *(const u32x4*)kn_g, rp = (u32x4){0, 0, 0, 0}, rv = *(const u32x4*)vt_g;
;     if (tid < 256) rp = *(const u32x4*)kp_g;
;     f32x16 o[2][2];
; #pragma unroll
;     for (int j = 0; j < 2; ++j)
; #pragma unroll
;         for (int i = 0; i < 16; ++i) { o[j][0][i] = 0.f; o[j][1][i] = 0.f; }
;     float mrun[2] = {0.f, 0.f}, lsum[2] = {0.f, 0.f};
;     __syncthreads();
;     *(LAS u32x4*)(Ks + kn_l) = rk; if (tid < 256) *(LAS u32x4*)(Ks + kp_l) = rp;
;     *(LAS u32x2*)(Vs + vt_l) = (u32x2){rv.x, rv.y}; *(LAS u32x2*)(Vs + vt_l + 8) = (u32x2){rv.z, rv.w};
;     __syncthreads();
.LBB0_1118:
	s_or_b64 exec, exec, s[6:7]
	s_movk_i32 s6, 0x88
	v_mul_lo_u32 v4, v9, s6
	v_add3_u32 v211, 0, v4, v8
	s_cmpk_gt_i32 s2, 0xff
	v_add_u32_e32 v4, 0x6800, v211
	s_cselect_b64 s[26:27], -1, 0
	s_cmpk_lt_i32 s2, 0x100
	s_mov_b64 s[6:7], -1
	s_waitcnt vmcnt(0)
	ds_write2_b64 v4, v[0:1], v[2:3] offset1:1
	v_lshrrev_b32_e32 v40, 6, v232
	v_mul_u32_u24_e32 v40, 0x2400, v40
	v_add_u32_e32 v40, 0xc000, v40
	v_lshl_add_u32 v41, v233, 4, v40
	v_and_b32_e32 v42, 31, v233
	v_mul_u32_u24_e32 v42, 0xc0, v42
	v_add_u32_e32 v42, v42, v40
	v_lshrrev_b32_e32 v43, 5, v233
	v_lshl_add_u32 v42, v43, 4, v42
	ds_write_b128 v41, v[80:83]
	ds_write_b128 v41, v[84:87] offset:1024
	ds_write_b128 v41, v[88:91] offset:2048
	ds_write_b128 v41, v[92:95] offset:3072
	ds_write_b128 v41, v[96:99] offset:4096
	ds_write_b128 v41, v[100:103] offset:5120
	ds_read_b128 v[172:175], v42
	ds_read_b128 v[128:131], v42 offset:32
	ds_read_b128 v[132:135], v42 offset:64
	ds_read_b128 v[136:139], v42 offset:96
	ds_read_b128 v[140:143], v42 offset:128
	ds_read_b128 v[144:147], v42 offset:160
	ds_write_b128 v41, v[104:107]
	ds_write_b128 v41, v[108:111] offset:1024
	ds_write_b128 v41, v[112:115] offset:2048
	ds_write_b128 v41, v[116:119] offset:3072
	ds_write_b128 v41, v[120:123] offset:4096
	ds_write_b128 v41, v[124:127] offset:5120
	ds_read_b128 v[148:151], v42
	ds_read_b128 v[152:155], v42 offset:32
	ds_read_b128 v[156:159], v42 offset:64
	ds_read_b128 v[160:163], v42 offset:96
	ds_read_b128 v[164:167], v42 offset:128
	ds_read_b128 v[168:171], v42 offset:160
	s_waitcnt lgkmcnt(0)
	s_barrier
	v_mov_b32_e32 v250, 0x700
	s_mov_b32 s19, 0x800000
	v_readlane_b32 s42, v254, 58
	v_readlane_b32 s43, v254, 59
	s_movk_i32 s0, 0xd0
	v_mad_u32_u24 v227, v226, s0, 0
	v_lshl_add_u32 v239, v68, 4, v227
	v_add_u32_e32 v243, 0x1000, v64
	v_add_u32_e32 v242, v223, v224
	v_add3_u32 v216, v220, v219, 64
	v_add_u32_e32 v188, 0x1000, v188
	v_mul_i32_i24_e32 v32, 0xffffffb8, v226
	v_lshlrev_b32_e32 v33, 3, v68
	v_add3_u32 v241, v227, v32, v33
	v_and_b32_e32 v65, 64, v233
	v_xor_b32_e32 v64, 32, v233
	v_add_u32_e32 v65, 64, v65
	v_cmp_lt_i32_e32 vcc, v64, v65
	s_nop 1
	v_cndmask_b32_e32 v64, v233, v64, vcc
	v_lshlrev_b32_e32 v240, 2, v64
	v_mov_b32_e32 v0, 0
	v_mov_b32_e32 v1, 0
	v_mov_b32_e32 v2, 0
	v_mov_b32_e32 v3, 0
	v_mov_b32_e32 v4, 0
	v_mov_b32_e32 v5, 0
	v_mov_b32_e32 v6, 0
	v_mov_b32_e32 v7, 0
	v_mov_b32_e32 v8, 0
	v_mov_b32_e32 v9, 0
	v_mov_b32_e32 v10, 0
	v_mov_b32_e32 v11, 0
	v_mov_b32_e32 v12, 0
	v_mov_b32_e32 v13, 0
	v_mov_b32_e32 v14, 0
	v_mov_b32_e32 v15, 0
	v_mov_b32_e32 v16, 0
	v_mov_b32_e32 v17, 0
	v_mov_b32_e32 v18, 0
	v_mov_b32_e32 v19, 0
	v_mov_b32_e32 v20, 0
	v_mov_b32_e32 v21, 0
	v_mov_b32_e32 v22, 0
	v_mov_b32_e32 v23, 0
	v_mov_b32_e32 v24, 0
	v_mov_b32_e32 v25, 0
	v_mov_b32_e32 v26, 0
	v_mov_b32_e32 v27, 0
	v_mov_b32_e32 v28, 0
	v_mov_b32_e32 v29, 0
	v_mov_b32_e32 v30, 0
	v_mov_b32_e32 v31, 0
	v_mov_b32_e32 v32, 0
	v_mov_b32_e32 v33, 0
	v_mov_b32_e32 v34, 0
	v_mov_b32_e32 v35, 0
	v_mov_b32_e32 v36, 0
	v_mov_b32_e32 v37, 0
	v_mov_b32_e32 v38, 0
	v_mov_b32_e32 v39, 0
	v_mov_b32_e32 v40, 0
	v_mov_b32_e32 v41, 0
	v_mov_b32_e32 v42, 0
	v_mov_b32_e32 v43, 0
	v_mov_b32_e32 v44, 0
	v_mov_b32_e32 v45, 0
	v_mov_b32_e32 v46, 0
	v_mov_b32_e32 v47, 0
	v_mov_b32_e32 v48, 0
	v_mov_b32_e32 v49, 0
	v_mov_b32_e32 v50, 0
	v_mov_b32_e32 v51, 0
	v_mov_b32_e32 v52, 0
	v_mov_b32_e32 v53, 0
	v_mov_b32_e32 v54, 0
	v_mov_b32_e32 v55, 0
	v_mov_b32_e32 v56, 0
	v_mov_b32_e32 v57, 0
	v_mov_b32_e32 v58, 0
	v_mov_b32_e32 v59, 0
	v_mov_b32_e32 v60, 0
	v_mov_b32_e32 v61, 0
	v_mov_b32_e32 v62, 0
	v_mov_b32_e32 v63, 0
	v_mov_b32_e32 v212, 0
	v_mov_b32_e32 v213, 0
	v_mov_b32_e32 v214, 0
	v_mov_b32_e32 v215, 0
	s_mov_b32 s28, 0
	s_mov_b32 s29, 0xfffff800
	s_mov_b32 s100, 0xff800000
	s_and_b64 vcc, exec, s[26:27]
	s_cbranch_vccz .Lat_loop
	v_mov_b32_e32 v217, v189
	v_lshl_add_u64 v[180:181], v[188:189], 1, s[20:21]
	v_lshl_add_u64 v[184:185], v[216:217], 1, s[24:25]
	global_load_dwordx4 v[180:183], v[180:181], off
	s_nop 0
	global_load_dwordx4 v[184:187], v[184:185], off
	s_barrier
